# cache policy: nt on the prep-phase x loads and on the final output stores (once-touched streams)
# speedup vs baseline: 1.0133x; 1.0044x over previous
; __device__ void phase_prep(const P& p) {
;     ...
;   for (int row = (blockIdx.x * 8 + wid) * 2; row < NTOK; row += gridDim.x * 16) {
;     const float4* src0 = (const float4*)xrow(p, row);
;     const float4* src1 = (const float4*)xrow(p, row + 1);
;     float4 v0[4], v1[4];
; #pragma unroll
;     for (int i = 0; i < 4; ++i) { v0[i] = src0[lane + i * 64]; v1[i] = src1[lane + i * 64]; }
;     float ss0 = 0.f, ss1 = 0.f;
;     uint2* dst0 = (uint2*)(xb + (size_t)row * 1024);
;     uint2* dst1 = (uint2*)(xb + (size_t)(row + 1) * 1024);
; #pragma unroll
;     for (int i = 0; i < 4; ++i) {
;       ss0 += v0[i].x * v0[i].x + v0[i].y * v0[i].y + v0[i].z * v0[i].z + v0[i].w * v0[i].w;
;       ss1 += v1[i].x * v1[i].x + v1[i].y * v1[i].y + v1[i].z * v1[i].z + v1[i].w * v1[i].w;
;       uint2 o; o.x = pack2(v0[i].x, v0[i].y); o.y = pack2(v0[i].z, v0[i].w); dst0[lane + i * 64] = o;
;       o.x = pack2(v1[i].x, v1[i].y); o.y = pack2(v1[i].z, v1[i].w); dst1[lane + i * 64] = o;
;     }
; #pragma unroll
;     for (int s2 = 32; s2 >= 1; s2 >>= 1) { ss0 += __shfl_xor(ss0, s2); ss1 += __shfl_xor(ss1, s2); }
;     if (lane == 0) { rs1[row] = rsqrtf(ss0 * (1.f / 1024.f) + 1e-6f); rs1[row + 1] = rsqrtf(ss1 * (1.f / 1024.f) + 1e-6f); }
.LBB0_27:
	v_add_u32_e32 v12, 0xffff8000, v4
	v_ashrrev_i32_e32 v5, 31, v4
	v_cmp_gt_i32_e64 s[0:1], s13, v4
	v_add_u32_e32 v38, 0xffff8001, v4
	v_lshlrev_b64 v[54:55], 11, v[4:5]
	v_cndmask_b32_e64 v13, 0, v5, s[0:1]
	v_cndmask_b32_e64 v12, v12, v4, s[0:1]
	v_cndmask_b32_e64 v15, v21, v23, s[0:1]
	v_cndmask_b32_e64 v14, v24, v25, s[0:1]
	v_lshlrev_b64 v[12:13], 12, v[12:13]
	v_lshl_add_u64 v[12:13], v[14:15], 0, v[12:13]
	v_lshl_add_u64 v[34:35], v[12:13], 0, v[6:7]
	v_add_u32_e32 v12, 1, v4
	v_ashrrev_i32_e32 v13, 31, v12
	v_cmp_gt_i32_e64 s[0:1], s13, v12
	s_waitcnt lgkmcnt(0)
	global_load_dwordx4 v[14:17], v[34:35], off nt
	global_load_dwordx4 v[26:29], v[34:35], off offset:1024 nt
	v_cndmask_b32_e64 v39, 0, v13, s[0:1]
	v_cndmask_b32_e64 v38, v38, v12, s[0:1]
	v_cndmask_b32_e64 v41, v21, v23, s[0:1]
	v_cndmask_b32_e64 v40, v24, v25, s[0:1]
	v_lshlrev_b64 v[38:39], 12, v[38:39]
	v_lshl_add_u64 v[38:39], v[40:41], 0, v[38:39]
	v_lshl_add_u64 v[50:51], v[38:39], 0, v[6:7]
	global_load_dwordx4 v[30:33], v[34:35], off offset:2048 nt
	s_nop 0
	global_load_dwordx4 v[34:37], v[34:35], off offset:3072 nt
	s_nop 0
	global_load_dwordx4 v[38:41], v[50:51], off nt
	global_load_dwordx4 v[42:45], v[50:51], off offset:1024 nt
	global_load_dwordx4 v[46:49], v[50:51], off offset:2048 nt
	s_nop 0
	global_load_dwordx4 v[50:53], v[50:51], off offset:3072 nt
	v_lshl_add_u64 v[54:55], v[8:9], 0, v[54:55]
	v_lshlrev_b64 v[56:57], 11, v[12:13]
	v_lshl_add_u64 v[56:57], v[8:9], 0, v[56:57]
	s_waitcnt vmcnt(7)
	v_mov_b32_e32 v61, v15
	s_waitcnt vmcnt(6)
	v_mov_b32_e32 v69, v27
	v_mov_b32_e32 v59, v14
	v_mov_b32_e32 v67, v26
	v_mov_b32_e32 v63, v16
	v_mov_b32_e32 v79, v28
	v_mov_b32_e32 v65, v17
	s_waitcnt vmcnt(3)
	v_mov_b32_e32 v60, v39
	s_waitcnt vmcnt(2)
	v_mov_b32_e32 v68, v43
	v_mov_b32_e32 v73, v31
	v_mov_b32_e32 v58, v38
	v_mov_b32_e32 v66, v42
	s_waitcnt vmcnt(1)
	v_mov_b32_e32 v72, v47
	v_pk_mul_f32 v[60:61], v[60:61], v[60:61]
	v_pk_mul_f32 v[68:69], v[68:69], v[68:69]
	v_mov_b32_e32 v71, v30
	v_mov_b32_e32 v77, v35
	v_mov_b32_e32 v70, v46
	s_waitcnt vmcnt(0)
	v_mov_b32_e32 v76, v51
	v_mov_b32_e32 v62, v40
	v_mov_b32_e32 v78, v44
	v_pk_mul_f32 v[72:73], v[72:73], v[72:73]
	v_pk_fma_f32 v[58:59], v[58:59], v[58:59], v[60:61]
	v_pk_fma_f32 v[60:61], v[66:67], v[66:67], v[68:69]
	v_mov_b32_e32 v75, v34
	v_mov_b32_e32 v81, v32
	v_mov_b32_e32 v85, v29
	v_mov_b32_e32 v74, v50
	v_mov_b32_e32 v80, v48
	v_mov_b32_e32 v64, v41
	v_mov_b32_e32 v84, v45
	v_pk_mul_f32 v[76:77], v[76:77], v[76:77]
	v_pk_fma_f32 v[66:67], v[70:71], v[70:71], v[72:73]
	v_pk_fma_f32 v[58:59], v[62:63], v[62:63], v[58:59]
	v_pk_fma_f32 v[60:61], v[78:79], v[78:79], v[60:61]
	v_mov_b32_e32 v83, v36
	v_mov_b32_e32 v87, v33
	v_mov_b32_e32 v82, v52
	v_mov_b32_e32 v86, v49
	v_pk_fma_f32 v[68:69], v[74:75], v[74:75], v[76:77]
	v_pk_fma_f32 v[62:63], v[80:81], v[80:81], v[66:67]
	v_pk_fma_f32 v[58:59], v[64:65], v[64:65], v[58:59]
	v_pk_fma_f32 v[60:61], v[84:85], v[84:85], v[60:61]
	v_cvt_pk_bf16_f32 v89, v36, v37
	v_mov_b32_e32 v36, v53
	v_pk_fma_f32 v[66:67], v[82:83], v[82:83], v[68:69]
	v_pk_fma_f32 v[62:63], v[86:87], v[86:87], v[62:63]
	v_pk_add_f32 v[58:59], v[58:59], v[60:61]
	v_pk_fma_f32 v[36:37], v[36:37], v[36:37], v[66:67]
	v_pk_add_f32 v[58:59], v[58:59], v[62:63]
	v_cvt_pk_bf16_f32 v14, v14, v15
	v_pk_add_f32 v[36:37], v[58:59], v[36:37]
	ds_bpermute_b32 v59, v1, v37
	ds_bpermute_b32 v58, v1, v36
	v_cvt_pk_bf16_f32 v15, v16, v17
	v_cvt_pk_bf16_f32 v16, v26, v27
	v_cvt_pk_bf16_f32 v17, v28, v29
	v_cvt_pk_bf16_f32 v28, v30, v31
	s_waitcnt lgkmcnt(0)
	v_pk_add_f32 v[26:27], v[36:37], v[58:59]
	ds_bpermute_b32 v37, v3, v27
	ds_bpermute_b32 v36, v3, v26
	global_store_dwordx2 v[54:55], v[14:15], off
	global_store_dwordx2 v[54:55], v[16:17], off offset:512
	v_cvt_pk_bf16_f32 v29, v32, v33
	v_cvt_pk_bf16_f32 v88, v34, v35
	v_cvt_pk_bf16_f32 v32, v38, v39
	s_waitcnt lgkmcnt(0)
	v_pk_add_f32 v[26:27], v[26:27], v[36:37]
	ds_bpermute_b32 v31, v11, v27
	ds_bpermute_b32 v30, v11, v26
	v_cvt_pk_bf16_f32 v33, v40, v41
	v_cvt_pk_bf16_f32 v34, v42, v43
	v_cvt_pk_bf16_f32 v35, v44, v45
	v_cvt_pk_bf16_f32 v36, v46, v47
	s_waitcnt lgkmcnt(0)
	v_pk_add_f32 v[26:27], v[26:27], v[30:31]
	ds_bpermute_b32 v31, v18, v27
	ds_bpermute_b32 v30, v18, v26
	v_cvt_pk_bf16_f32 v37, v48, v49
	global_store_dwordx2 v[54:55], v[28:29], off offset:1024
	global_store_dwordx2 v[56:57], v[32:33], off
	global_store_dwordx2 v[56:57], v[34:35], off offset:512
	global_store_dwordx2 v[56:57], v[36:37], off offset:1024
	global_store_dwordx2 v[54:55], v[88:89], off offset:1536
	s_waitcnt lgkmcnt(0)
	v_pk_add_f32 v[14:15], v[26:27], v[30:31]
	ds_bpermute_b32 v17, v19, v15
	ds_bpermute_b32 v16, v19, v14
	v_cvt_pk_bf16_f32 v26, v50, v51
	v_cvt_pk_bf16_f32 v27, v52, v53
	global_store_dwordx2 v[56:57], v[26:27], off offset:1536
	s_waitcnt lgkmcnt(0)
	v_pk_add_f32 v[14:15], v[14:15], v[16:17]
	ds_bpermute_b32 v17, v20, v15
	ds_bpermute_b32 v16, v20, v14
	s_and_saveexec_b64 s[14:15], vcc
	s_cbranch_execz .LBB0_26
	s_waitcnt lgkmcnt(0)
	v_pk_add_f32 v[14:15], v[14:15], v[16:17]
	v_lshl_add_u64 v[26:27], v[4:5], 2, s[72:73]
	v_pk_fma_f32 v[14:15], v[14:15], s[12:13], v[10:11] op_sel_hi:[1,0,0]
	v_lshl_add_u64 v[12:13], v[12:13], 2, s[72:73]
	v_mul_f32_e32 v5, 0x4b800000, v15
	v_cmp_gt_f32_e64 s[0:1], s16, v15
	v_cmp_gt_f32_e64 s[4:5], s16, v14
	s_nop 0
	v_cndmask_b32_e64 v5, v15, v5, s[0:1]
	v_rsq_f32_e32 v5, v5
	v_mul_f32_e32 v15, 0x4b800000, v14
	v_cndmask_b32_e64 v14, v14, v15, s[4:5]
	v_rsq_f32_e32 v14, v14
	v_mul_f32_e32 v15, 0x45800000, v5
	v_cndmask_b32_e64 v5, v5, v15, s[0:1]
	global_store_dword v[26:27], v5, off
	v_mul_f32_e32 v5, 0x45800000, v14
	v_cndmask_b32_e64 v5, v14, v5, s[4:5]
	global_store_dword v[12:13], v5, off
	s_branch .LBB0_26

; __device__ __forceinline__ void store_rm4_f32(float* base, size_t ld, int c, bool odd, float v0, float v1, float v2, float v3) {
;   {
;     float r = dpp_swap1(odd ? v0 : v1);
;     float2 w; w.x = odd ? r : v0; w.y = odd ? v1 : r;
;     *(float2*)(base + (size_t)(odd ? 1 : 0) * ld + (c - (odd ? 1 : 0))) = w;
;   }
;   {
;     float r = dpp_swap1(odd ? v2 : v3);
;     float2 w; w.x = odd ? r : v2; w.y = odd ? v3 : r;
;     *(float2*)(base + (size_t)(2 + (odd ? 1 : 0)) * ld + (c - (odd ? 1 : 0))) = w;
;   }
; }
;   __device__ __forceinline__ void operator()(f32x4 (&acc)[2][2][4][2], int brow, int bcol, int wr, int wc, int fr, int fq) const {
;     ...
; #pragma unroll
;     for (int ai = 0; ai < 2; ++ai)
; #pragma unroll
;       for (int m = 0; m < 4; ++m) {
;         int rl0 = ai * 128 + wr * 64 + m * 16 + fq * 4;
;         float4 r4 = *(const float4*)(rsl + rl0);
;         float rr[4] = {r4.x, r4.y, r4.z, r4.w};
; #pragma unroll
;         for (int bj = 0; bj < 2; ++bj)
; #pragma unroll
;           for (int n = 0; n < 2; ++n) {
;             int c = bcol + bj * 128 + wc * 32 + n * 16 + fr;
;             float gf = p.g_final[c];
;             store_rm4_f32(p.out + (size_t)(brow + rl0) * 1024, 1024, c, fr & 1, acc[ai][bj][m][n][0] * rr[0] * gf,
;                           acc[ai][bj][m][n][1] * rr[1] * gf, acc[ai][bj][m][n][2] * rr[2] * gf, acc[ai][bj][m][n][3] * rr[3] * gf);
;           }
;         __builtin_amdgcn_sched_barrier(0);
;       }
.LBB0_650:
	s_or_b64 exec, exec, s[18:19]
	s_waitcnt lgkmcnt(0)
	s_barrier
	v_mbcnt_lo_u32_b32 v132, -1, 0
	v_mbcnt_hi_u32_b32 v132, -1, v132
	v_and_b32_e32 v133, 15, v132
	v_lshrrev_b32_e32 v134, 4, v132
	v_and_b32_e32 v136, 1, v132
	s_lshr_b32 s2, s33, 8
	s_lshl_b32 s2, s2, 6
	s_bfe_u32 s3, s33, 0x20006
	v_lshl_add_u32 v157, v134, 2, s2
	v_lshlrev_b32_e32 v156, 2, v157
	v_add_u32_e32 v156, 16, v156
	ds_read_b128 v[176:179], v156 offset:53248
	ds_read_b128 v[180:183], v156 offset:53312
	ds_read_b128 v[184:187], v156 offset:53376
	ds_read_b128 v[188:191], v156 offset:53440
	ds_read_b128 v[192:195], v156 offset:53760
	ds_read_b128 v[196:199], v156 offset:53824
	ds_read_b128 v[200:203], v156 offset:53888
	ds_read_b128 v[204:207], v156 offset:53952
	s_lshl_b32 s3, s3, 5
	s_add_i32 s3, s3, s59
	v_add_u32_e32 v158, s3, v133
	v_lshlrev_b32_e32 v158, 2, v158
	global_load_dword v208, v158, s[48:49]
	global_load_dword v209, v158, s[48:49] offset:64
	global_load_dword v210, v158, s[48:49] offset:512
	global_load_dword v211, v158, s[48:49] offset:576
	v_add_u32_e32 v157, v157, v136
	v_lshlrev_b32_e32 v137, 12, v157
	v_and_b32_e32 v157, 14, v133
	v_add_u32_e32 v157, s3, v157
	v_lshl_add_u32 v137, v157, 2, v137
	s_lshl_b32 s2, s58, 12
	s_add_u32 s100, s50, s2
	s_addc_u32 s101, s51, 0
	v_cmp_eq_u32_e32 vcc, 1, v136
	s_waitcnt vmcnt(0) lgkmcnt(0)
	v_mul_f32_e32 v212, v112, v176
	v_mul_f32_e32 v213, v113, v177
	v_mul_f32_e32 v214, v114, v178
	v_mul_f32_e32 v215, v115, v179
	v_mul_f32_e32 v216, v116, v176
	v_mul_f32_e32 v217, v117, v177
	v_mul_f32_e32 v218, v118, v178
	v_mul_f32_e32 v219, v119, v179
	v_mul_f32_e32 v220, v124, v176
	v_mul_f32_e32 v221, v125, v177
	v_mul_f32_e32 v222, v126, v178
	v_mul_f32_e32 v223, v127, v179
	v_mul_f32_e32 v224, v120, v176
	v_mul_f32_e32 v225, v121, v177
	v_mul_f32_e32 v226, v122, v178
	v_mul_f32_e32 v227, v123, v179
	v_mul_f32_e32 v212, v212, v208
	v_mul_f32_e32 v213, v213, v208
	v_mul_f32_e32 v214, v214, v208
	v_mul_f32_e32 v215, v215, v208
	v_mul_f32_e32 v216, v216, v209
	v_mul_f32_e32 v217, v217, v209
	v_mul_f32_e32 v218, v218, v209
	v_mul_f32_e32 v219, v219, v209
	v_mul_f32_e32 v220, v220, v210
	v_mul_f32_e32 v221, v221, v210
	v_mul_f32_e32 v222, v222, v210
	v_mul_f32_e32 v223, v223, v210
	v_mul_f32_e32 v224, v224, v211
	v_mul_f32_e32 v225, v225, v211
	v_mul_f32_e32 v226, v226, v211
	v_mul_f32_e32 v227, v227, v211
	v_cndmask_b32_e32 v228, v213, v212, vcc
	v_cndmask_b32_e32 v229, v215, v214, vcc
	v_cndmask_b32_e32 v230, v217, v216, vcc
	v_cndmask_b32_e32 v231, v219, v218, vcc
	v_cndmask_b32_e32 v232, v221, v220, vcc
	v_cndmask_b32_e32 v233, v223, v222, vcc
	v_cndmask_b32_e32 v234, v225, v224, vcc
	v_cndmask_b32_e32 v235, v227, v226, vcc
	v_mov_b32_dpp v228, v228 quad_perm:[1,0,3,2] row_mask:0xf bank_mask:0xf bound_ctrl:1
	v_mov_b32_dpp v229, v229 quad_perm:[1,0,3,2] row_mask:0xf bank_mask:0xf bound_ctrl:1
	v_mov_b32_dpp v230, v230 quad_perm:[1,0,3,2] row_mask:0xf bank_mask:0xf bound_ctrl:1
	v_mov_b32_dpp v231, v231 quad_perm:[1,0,3,2] row_mask:0xf bank_mask:0xf bound_ctrl:1
	v_mov_b32_dpp v232, v232 quad_perm:[1,0,3,2] row_mask:0xf bank_mask:0xf bound_ctrl:1
	v_mov_b32_dpp v233, v233 quad_perm:[1,0,3,2] row_mask:0xf bank_mask:0xf bound_ctrl:1
	v_mov_b32_dpp v234, v234 quad_perm:[1,0,3,2] row_mask:0xf bank_mask:0xf bound_ctrl:1
	v_mov_b32_dpp v235, v235 quad_perm:[1,0,3,2] row_mask:0xf bank_mask:0xf bound_ctrl:1
	v_cndmask_b32_e32 v212, v212, v228, vcc
	v_cndmask_b32_e32 v213, v228, v213, vcc
	v_cndmask_b32_e32 v214, v214, v229, vcc
	v_cndmask_b32_e32 v215, v229, v215, vcc
	v_cndmask_b32_e32 v216, v216, v230, vcc
	v_cndmask_b32_e32 v217, v230, v217, vcc
	v_cndmask_b32_e32 v218, v218, v231, vcc
	v_cndmask_b32_e32 v219, v231, v219, vcc
	v_cndmask_b32_e32 v220, v220, v232, vcc
	v_cndmask_b32_e32 v221, v232, v221, vcc
	v_cndmask_b32_e32 v222, v222, v233, vcc
	v_cndmask_b32_e32 v223, v233, v223, vcc
	v_cndmask_b32_e32 v224, v224, v234, vcc
	v_cndmask_b32_e32 v225, v234, v225, vcc
	v_cndmask_b32_e32 v226, v226, v235, vcc
	v_cndmask_b32_e32 v227, v235, v227, vcc
	v_mov_b32_e32 v138, v137
	v_add_u32_e32 v139, 0x2000, v137
	global_store_dwordx2 v138, v[212:213], s[100:101] nt
	global_store_dwordx2 v139, v[214:215], s[100:101] nt
	global_store_dwordx2 v138, v[216:217], s[100:101] offset:64 nt
	global_store_dwordx2 v139, v[218:219], s[100:101] offset:64 nt
	global_store_dwordx2 v138, v[220:221], s[100:101] offset:512 nt
	global_store_dwordx2 v139, v[222:223], s[100:101] offset:512 nt
	global_store_dwordx2 v138, v[224:225], s[100:101] offset:576 nt
	global_store_dwordx2 v139, v[226:227], s[100:101] offset:576 nt
	v_mul_f32_e32 v212, v96, v180
	v_mul_f32_e32 v213, v97, v181
	v_mul_f32_e32 v214, v98, v182
	v_mul_f32_e32 v215, v99, v183
	v_mul_f32_e32 v216, v100, v180
	v_mul_f32_e32 v217, v101, v181
	v_mul_f32_e32 v218, v102, v182
	v_mul_f32_e32 v219, v103, v183
	v_mul_f32_e32 v220, v108, v180
	v_mul_f32_e32 v221, v109, v181
	v_mul_f32_e32 v222, v110, v182
	v_mul_f32_e32 v223, v111, v183
	v_mul_f32_e32 v224, v104, v180
	v_mul_f32_e32 v225, v105, v181
	v_mul_f32_e32 v226, v106, v182
	v_mul_f32_e32 v227, v107, v183
	v_mul_f32_e32 v212, v212, v208
	v_mul_f32_e32 v213, v213, v208
	v_mul_f32_e32 v214, v214, v208
	v_mul_f32_e32 v215, v215, v208
	v_mul_f32_e32 v216, v216, v209
	v_mul_f32_e32 v217, v217, v209
	v_mul_f32_e32 v218, v218, v209
	v_mul_f32_e32 v219, v219, v209
	v_mul_f32_e32 v220, v220, v210
	v_mul_f32_e32 v221, v221, v210
	v_mul_f32_e32 v222, v222, v210
	v_mul_f32_e32 v223, v223, v210
	v_mul_f32_e32 v224, v224, v211
	v_mul_f32_e32 v225, v225, v211
	v_mul_f32_e32 v226, v226, v211
	v_mul_f32_e32 v227, v227, v211
; __device__ __forceinline__ void store_rm4_f32(float* base, size_t ld, int c, bool odd, float v0, float v1, float v2, float v3) {
;   {
;     float r = dpp_swap1(odd ? v0 : v1);
;     float2 w; w.x = odd ? r : v0; w.y = odd ? v1 : r;
;     *(float2*)(base + (size_t)(odd ? 1 : 0) * ld + (c - (odd ? 1 : 0))) = w;
;   }
;   {
;     float r = dpp_swap1(odd ? v2 : v3);
;     float2 w; w.x = odd ? r : v2; w.y = odd ? v3 : r;
;     *(float2*)(base + (size_t)(2 + (odd ? 1 : 0)) * ld + (c - (odd ? 1 : 0))) = w;
;   }
; }
;   __device__ __forceinline__ void operator()(f32x4 (&acc)[2][2][4][2], int brow, int bcol, int wr, int wc, int fr, int fq) const {
;     ...
; #pragma unroll
;     for (int ai = 0; ai < 2; ++ai)
; #pragma unroll
;       for (int m = 0; m < 4; ++m) {
;         int rl0 = ai * 128 + wr * 64 + m * 16 + fq * 4;
;         float4 r4 = *(const float4*)(rsl + rl0);
;         float rr[4] = {r4.x, r4.y, r4.z, r4.w};
; #pragma unroll
;         for (int bj = 0; bj < 2; ++bj)
; #pragma unroll
;           for (int n = 0; n < 2; ++n) {
;             int c = bcol + bj * 128 + wc * 32 + n * 16 + fr;
;             float gf = p.g_final[c];
;             store_rm4_f32(p.out + (size_t)(brow + rl0) * 1024, 1024, c, fr & 1, acc[ai][bj][m][n][0] * rr[0] * gf,
;                           acc[ai][bj][m][n][1] * rr[1] * gf, acc[ai][bj][m][n][2] * rr[2] * gf, acc[ai][bj][m][n][3] * rr[3] * gf);
;           }
;         __builtin_amdgcn_sched_barrier(0);
;       }
	v_cndmask_b32_e32 v228, v213, v212, vcc
	v_cndmask_b32_e32 v229, v215, v214, vcc
	v_cndmask_b32_e32 v230, v217, v216, vcc
	v_cndmask_b32_e32 v231, v219, v218, vcc
	v_cndmask_b32_e32 v232, v221, v220, vcc
	v_cndmask_b32_e32 v233, v223, v222, vcc
	v_cndmask_b32_e32 v234, v225, v224, vcc
	v_cndmask_b32_e32 v235, v227, v226, vcc
	v_mov_b32_dpp v228, v228 quad_perm:[1,0,3,2] row_mask:0xf bank_mask:0xf bound_ctrl:1
	v_mov_b32_dpp v229, v229 quad_perm:[1,0,3,2] row_mask:0xf bank_mask:0xf bound_ctrl:1
	v_mov_b32_dpp v230, v230 quad_perm:[1,0,3,2] row_mask:0xf bank_mask:0xf bound_ctrl:1
	v_mov_b32_dpp v231, v231 quad_perm:[1,0,3,2] row_mask:0xf bank_mask:0xf bound_ctrl:1
	v_mov_b32_dpp v232, v232 quad_perm:[1,0,3,2] row_mask:0xf bank_mask:0xf bound_ctrl:1
	v_mov_b32_dpp v233, v233 quad_perm:[1,0,3,2] row_mask:0xf bank_mask:0xf bound_ctrl:1
	v_mov_b32_dpp v234, v234 quad_perm:[1,0,3,2] row_mask:0xf bank_mask:0xf bound_ctrl:1
	v_mov_b32_dpp v235, v235 quad_perm:[1,0,3,2] row_mask:0xf bank_mask:0xf bound_ctrl:1
	v_cndmask_b32_e32 v212, v212, v228, vcc
	v_cndmask_b32_e32 v213, v228, v213, vcc
	v_cndmask_b32_e32 v214, v214, v229, vcc
	v_cndmask_b32_e32 v215, v229, v215, vcc
	v_cndmask_b32_e32 v216, v216, v230, vcc
	v_cndmask_b32_e32 v217, v230, v217, vcc
	v_cndmask_b32_e32 v218, v218, v231, vcc
	v_cndmask_b32_e32 v219, v231, v219, vcc
	v_cndmask_b32_e32 v220, v220, v232, vcc
	v_cndmask_b32_e32 v221, v232, v221, vcc
	v_cndmask_b32_e32 v222, v222, v233, vcc
	v_cndmask_b32_e32 v223, v233, v223, vcc
	v_cndmask_b32_e32 v224, v224, v234, vcc
	v_cndmask_b32_e32 v225, v234, v225, vcc
	v_cndmask_b32_e32 v226, v226, v235, vcc
	v_cndmask_b32_e32 v227, v235, v227, vcc
	v_add_u32_e32 v138, 0x10000, v137
	v_add_u32_e32 v139, 0x12000, v137
	global_store_dwordx2 v138, v[212:213], s[100:101] nt
	global_store_dwordx2 v139, v[214:215], s[100:101] nt
	global_store_dwordx2 v138, v[216:217], s[100:101] offset:64 nt
	global_store_dwordx2 v139, v[218:219], s[100:101] offset:64 nt
	global_store_dwordx2 v138, v[220:221], s[100:101] offset:512 nt
	global_store_dwordx2 v139, v[222:223], s[100:101] offset:512 nt
	global_store_dwordx2 v138, v[224:225], s[100:101] offset:576 nt
	global_store_dwordx2 v139, v[226:227], s[100:101] offset:576 nt
	v_mul_f32_e32 v212, v80, v184
	v_mul_f32_e32 v213, v81, v185
	v_mul_f32_e32 v214, v82, v186
	v_mul_f32_e32 v215, v83, v187
	v_mul_f32_e32 v216, v84, v184
	v_mul_f32_e32 v217, v85, v185
	v_mul_f32_e32 v218, v86, v186
	v_mul_f32_e32 v219, v87, v187
	v_mul_f32_e32 v220, v92, v184
	v_mul_f32_e32 v221, v93, v185
	v_mul_f32_e32 v222, v94, v186
	v_mul_f32_e32 v223, v95, v187
	v_mul_f32_e32 v224, v88, v184
	v_mul_f32_e32 v225, v89, v185
	v_mul_f32_e32 v226, v90, v186
	v_mul_f32_e32 v227, v91, v187
	v_mul_f32_e32 v212, v212, v208
	v_mul_f32_e32 v213, v213, v208
	v_mul_f32_e32 v214, v214, v208
	v_mul_f32_e32 v215, v215, v208
	v_mul_f32_e32 v216, v216, v209
	v_mul_f32_e32 v217, v217, v209
	v_mul_f32_e32 v218, v218, v209
	v_mul_f32_e32 v219, v219, v209
	v_mul_f32_e32 v220, v220, v210
	v_mul_f32_e32 v221, v221, v210
	v_mul_f32_e32 v222, v222, v210
	v_mul_f32_e32 v223, v223, v210
	v_mul_f32_e32 v224, v224, v211
	v_mul_f32_e32 v225, v225, v211
	v_mul_f32_e32 v226, v226, v211
	v_mul_f32_e32 v227, v227, v211
	v_cndmask_b32_e32 v228, v213, v212, vcc
	v_cndmask_b32_e32 v229, v215, v214, vcc
	v_cndmask_b32_e32 v230, v217, v216, vcc
	v_cndmask_b32_e32 v231, v219, v218, vcc
	v_cndmask_b32_e32 v232, v221, v220, vcc
	v_cndmask_b32_e32 v233, v223, v222, vcc
	v_cndmask_b32_e32 v234, v225, v224, vcc
	v_cndmask_b32_e32 v235, v227, v226, vcc
	v_mov_b32_dpp v228, v228 quad_perm:[1,0,3,2] row_mask:0xf bank_mask:0xf bound_ctrl:1
	v_mov_b32_dpp v229, v229 quad_perm:[1,0,3,2] row_mask:0xf bank_mask:0xf bound_ctrl:1
	v_mov_b32_dpp v230, v230 quad_perm:[1,0,3,2] row_mask:0xf bank_mask:0xf bound_ctrl:1
	v_mov_b32_dpp v231, v231 quad_perm:[1,0,3,2] row_mask:0xf bank_mask:0xf bound_ctrl:1
	v_mov_b32_dpp v232, v232 quad_perm:[1,0,3,2] row_mask:0xf bank_mask:0xf bound_ctrl:1
	v_mov_b32_dpp v233, v233 quad_perm:[1,0,3,2] row_mask:0xf bank_mask:0xf bound_ctrl:1
	v_mov_b32_dpp v234, v234 quad_perm:[1,0,3,2] row_mask:0xf bank_mask:0xf bound_ctrl:1
	v_mov_b32_dpp v235, v235 quad_perm:[1,0,3,2] row_mask:0xf bank_mask:0xf bound_ctrl:1
	v_cndmask_b32_e32 v212, v212, v228, vcc
	v_cndmask_b32_e32 v213, v228, v213, vcc
	v_cndmask_b32_e32 v214, v214, v229, vcc
	v_cndmask_b32_e32 v215, v229, v215, vcc
	v_cndmask_b32_e32 v216, v216, v230, vcc
	v_cndmask_b32_e32 v217, v230, v217, vcc
	v_cndmask_b32_e32 v218, v218, v231, vcc
	v_cndmask_b32_e32 v219, v231, v219, vcc
	v_cndmask_b32_e32 v220, v220, v232, vcc
	v_cndmask_b32_e32 v221, v232, v221, vcc
	v_cndmask_b32_e32 v222, v222, v233, vcc
	v_cndmask_b32_e32 v223, v233, v223, vcc
	v_cndmask_b32_e32 v224, v224, v234, vcc
	v_cndmask_b32_e32 v225, v234, v225, vcc
	v_cndmask_b32_e32 v226, v226, v235, vcc
	v_cndmask_b32_e32 v227, v235, v227, vcc
	v_add_u32_e32 v138, 0x20000, v137
	v_add_u32_e32 v139, 0x22000, v137
	global_store_dwordx2 v138, v[212:213], s[100:101] nt
	global_store_dwordx2 v139, v[214:215], s[100:101] nt
	global_store_dwordx2 v138, v[216:217], s[100:101] offset:64 nt
	global_store_dwordx2 v139, v[218:219], s[100:101] offset:64 nt
	global_store_dwordx2 v138, v[220:221], s[100:101] offset:512 nt
	global_store_dwordx2 v139, v[222:223], s[100:101] offset:512 nt
	global_store_dwordx2 v138, v[224:225], s[100:101] offset:576 nt
	global_store_dwordx2 v139, v[226:227], s[100:101] offset:576 nt
	v_mul_f32_e32 v212, v64, v188
	v_mul_f32_e32 v213, v65, v189
	v_mul_f32_e32 v214, v66, v190
	v_mul_f32_e32 v215, v67, v191
	v_mul_f32_e32 v216, v68, v188
; __device__ __forceinline__ void store_rm4_f32(float* base, size_t ld, int c, bool odd, float v0, float v1, float v2, float v3) {
;   {
;     float r = dpp_swap1(odd ? v0 : v1);
;     float2 w; w.x = odd ? r : v0; w.y = odd ? v1 : r;
;     *(float2*)(base + (size_t)(odd ? 1 : 0) * ld + (c - (odd ? 1 : 0))) = w;
;   }
;   {
;     float r = dpp_swap1(odd ? v2 : v3);
;     float2 w; w.x = odd ? r : v2; w.y = odd ? v3 : r;
;     *(float2*)(base + (size_t)(2 + (odd ? 1 : 0)) * ld + (c - (odd ? 1 : 0))) = w;
;   }
; }
;   __device__ __forceinline__ void operator()(f32x4 (&acc)[2][2][4][2], int brow, int bcol, int wr, int wc, int fr, int fq) const {
;     ...
; #pragma unroll
;     for (int ai = 0; ai < 2; ++ai)
; #pragma unroll
;       for (int m = 0; m < 4; ++m) {
;         int rl0 = ai * 128 + wr * 64 + m * 16 + fq * 4;
;         float4 r4 = *(const float4*)(rsl + rl0);
;         float rr[4] = {r4.x, r4.y, r4.z, r4.w};
; #pragma unroll
;         for (int bj = 0; bj < 2; ++bj)
; #pragma unroll
;           for (int n = 0; n < 2; ++n) {
;             int c = bcol + bj * 128 + wc * 32 + n * 16 + fr;
;             float gf = p.g_final[c];
;             store_rm4_f32(p.out + (size_t)(brow + rl0) * 1024, 1024, c, fr & 1, acc[ai][bj][m][n][0] * rr[0] * gf,
;                           acc[ai][bj][m][n][1] * rr[1] * gf, acc[ai][bj][m][n][2] * rr[2] * gf, acc[ai][bj][m][n][3] * rr[3] * gf);
;           }
;         __builtin_amdgcn_sched_barrier(0);
;       }
	v_mul_f32_e32 v217, v69, v189
	v_mul_f32_e32 v218, v70, v190
	v_mul_f32_e32 v219, v71, v191
	v_mul_f32_e32 v220, v76, v188
	v_mul_f32_e32 v221, v77, v189
	v_mul_f32_e32 v222, v78, v190
	v_mul_f32_e32 v223, v79, v191
	v_mul_f32_e32 v224, v72, v188
	v_mul_f32_e32 v225, v73, v189
	v_mul_f32_e32 v226, v74, v190
	v_mul_f32_e32 v227, v75, v191
	v_mul_f32_e32 v212, v212, v208
	v_mul_f32_e32 v213, v213, v208
	v_mul_f32_e32 v214, v214, v208
	v_mul_f32_e32 v215, v215, v208
	v_mul_f32_e32 v216, v216, v209
	v_mul_f32_e32 v217, v217, v209
	v_mul_f32_e32 v218, v218, v209
	v_mul_f32_e32 v219, v219, v209
	v_mul_f32_e32 v220, v220, v210
	v_mul_f32_e32 v221, v221, v210
	v_mul_f32_e32 v222, v222, v210
	v_mul_f32_e32 v223, v223, v210
	v_mul_f32_e32 v224, v224, v211
	v_mul_f32_e32 v225, v225, v211
	v_mul_f32_e32 v226, v226, v211
	v_mul_f32_e32 v227, v227, v211
	v_cndmask_b32_e32 v228, v213, v212, vcc
	v_cndmask_b32_e32 v229, v215, v214, vcc
	v_cndmask_b32_e32 v230, v217, v216, vcc
	v_cndmask_b32_e32 v231, v219, v218, vcc
	v_cndmask_b32_e32 v232, v221, v220, vcc
	v_cndmask_b32_e32 v233, v223, v222, vcc
	v_cndmask_b32_e32 v234, v225, v224, vcc
	v_cndmask_b32_e32 v235, v227, v226, vcc
	v_mov_b32_dpp v228, v228 quad_perm:[1,0,3,2] row_mask:0xf bank_mask:0xf bound_ctrl:1
	v_mov_b32_dpp v229, v229 quad_perm:[1,0,3,2] row_mask:0xf bank_mask:0xf bound_ctrl:1
	v_mov_b32_dpp v230, v230 quad_perm:[1,0,3,2] row_mask:0xf bank_mask:0xf bound_ctrl:1
	v_mov_b32_dpp v231, v231 quad_perm:[1,0,3,2] row_mask:0xf bank_mask:0xf bound_ctrl:1
	v_mov_b32_dpp v232, v232 quad_perm:[1,0,3,2] row_mask:0xf bank_mask:0xf bound_ctrl:1
	v_mov_b32_dpp v233, v233 quad_perm:[1,0,3,2] row_mask:0xf bank_mask:0xf bound_ctrl:1
	v_mov_b32_dpp v234, v234 quad_perm:[1,0,3,2] row_mask:0xf bank_mask:0xf bound_ctrl:1
	v_mov_b32_dpp v235, v235 quad_perm:[1,0,3,2] row_mask:0xf bank_mask:0xf bound_ctrl:1
	v_cndmask_b32_e32 v212, v212, v228, vcc
	v_cndmask_b32_e32 v213, v228, v213, vcc
	v_cndmask_b32_e32 v214, v214, v229, vcc
	v_cndmask_b32_e32 v215, v229, v215, vcc
	v_cndmask_b32_e32 v216, v216, v230, vcc
	v_cndmask_b32_e32 v217, v230, v217, vcc
	v_cndmask_b32_e32 v218, v218, v231, vcc
	v_cndmask_b32_e32 v219, v231, v219, vcc
	v_cndmask_b32_e32 v220, v220, v232, vcc
	v_cndmask_b32_e32 v221, v232, v221, vcc
	v_cndmask_b32_e32 v222, v222, v233, vcc
	v_cndmask_b32_e32 v223, v233, v223, vcc
	v_cndmask_b32_e32 v224, v224, v234, vcc
	v_cndmask_b32_e32 v225, v234, v225, vcc
	v_cndmask_b32_e32 v226, v226, v235, vcc
	v_cndmask_b32_e32 v227, v235, v227, vcc
	v_add_u32_e32 v138, 0x30000, v137
	v_add_u32_e32 v139, 0x32000, v137
	global_store_dwordx2 v138, v[212:213], s[100:101] nt
	global_store_dwordx2 v139, v[214:215], s[100:101] nt
	global_store_dwordx2 v138, v[216:217], s[100:101] offset:64 nt
	global_store_dwordx2 v139, v[218:219], s[100:101] offset:64 nt
	global_store_dwordx2 v138, v[220:221], s[100:101] offset:512 nt
	global_store_dwordx2 v139, v[222:223], s[100:101] offset:512 nt
	global_store_dwordx2 v138, v[224:225], s[100:101] offset:576 nt
	global_store_dwordx2 v139, v[226:227], s[100:101] offset:576 nt
	v_mul_f32_e32 v212, v48, v192
	v_mul_f32_e32 v213, v49, v193
	v_mul_f32_e32 v214, v50, v194
	v_mul_f32_e32 v215, v51, v195
	v_mul_f32_e32 v216, v52, v192
	v_mul_f32_e32 v217, v53, v193
	v_mul_f32_e32 v218, v54, v194
	v_mul_f32_e32 v219, v55, v195
	v_mul_f32_e32 v220, v60, v192
	v_mul_f32_e32 v221, v61, v193
	v_mul_f32_e32 v222, v62, v194
	v_mul_f32_e32 v223, v63, v195
	v_mul_f32_e32 v224, v56, v192
	v_mul_f32_e32 v225, v57, v193
	v_mul_f32_e32 v226, v58, v194
	v_mul_f32_e32 v227, v59, v195
	v_mul_f32_e32 v212, v212, v208
	v_mul_f32_e32 v213, v213, v208
	v_mul_f32_e32 v214, v214, v208
	v_mul_f32_e32 v215, v215, v208
	v_mul_f32_e32 v216, v216, v209
	v_mul_f32_e32 v217, v217, v209
	v_mul_f32_e32 v218, v218, v209
	v_mul_f32_e32 v219, v219, v209
	v_mul_f32_e32 v220, v220, v210
	v_mul_f32_e32 v221, v221, v210
	v_mul_f32_e32 v222, v222, v210
	v_mul_f32_e32 v223, v223, v210
	v_mul_f32_e32 v224, v224, v211
	v_mul_f32_e32 v225, v225, v211
	v_mul_f32_e32 v226, v226, v211
	v_mul_f32_e32 v227, v227, v211
	v_cndmask_b32_e32 v228, v213, v212, vcc
	v_cndmask_b32_e32 v229, v215, v214, vcc
	v_cndmask_b32_e32 v230, v217, v216, vcc
	v_cndmask_b32_e32 v231, v219, v218, vcc
	v_cndmask_b32_e32 v232, v221, v220, vcc
	v_cndmask_b32_e32 v233, v223, v222, vcc
	v_cndmask_b32_e32 v234, v225, v224, vcc
	v_cndmask_b32_e32 v235, v227, v226, vcc
	v_mov_b32_dpp v228, v228 quad_perm:[1,0,3,2] row_mask:0xf bank_mask:0xf bound_ctrl:1
	v_mov_b32_dpp v229, v229 quad_perm:[1,0,3,2] row_mask:0xf bank_mask:0xf bound_ctrl:1
	v_mov_b32_dpp v230, v230 quad_perm:[1,0,3,2] row_mask:0xf bank_mask:0xf bound_ctrl:1
	v_mov_b32_dpp v231, v231 quad_perm:[1,0,3,2] row_mask:0xf bank_mask:0xf bound_ctrl:1
	v_mov_b32_dpp v232, v232 quad_perm:[1,0,3,2] row_mask:0xf bank_mask:0xf bound_ctrl:1
	v_mov_b32_dpp v233, v233 quad_perm:[1,0,3,2] row_mask:0xf bank_mask:0xf bound_ctrl:1
	v_mov_b32_dpp v234, v234 quad_perm:[1,0,3,2] row_mask:0xf bank_mask:0xf bound_ctrl:1
	v_mov_b32_dpp v235, v235 quad_perm:[1,0,3,2] row_mask:0xf bank_mask:0xf bound_ctrl:1
	v_cndmask_b32_e32 v212, v212, v228, vcc
	v_cndmask_b32_e32 v213, v228, v213, vcc
	v_cndmask_b32_e32 v214, v214, v229, vcc
	v_cndmask_b32_e32 v215, v229, v215, vcc
	v_cndmask_b32_e32 v216, v216, v230, vcc
	v_cndmask_b32_e32 v217, v230, v217, vcc
	v_cndmask_b32_e32 v218, v218, v231, vcc
	v_cndmask_b32_e32 v219, v231, v219, vcc
	v_cndmask_b32_e32 v220, v220, v232, vcc
	v_cndmask_b32_e32 v221, v232, v221, vcc
	v_cndmask_b32_e32 v222, v222, v233, vcc
	v_cndmask_b32_e32 v223, v233, v223, vcc
	v_cndmask_b32_e32 v224, v224, v234, vcc
; __device__ __forceinline__ void store_rm4_f32(float* base, size_t ld, int c, bool odd, float v0, float v1, float v2, float v3) {
;   {
;     float r = dpp_swap1(odd ? v0 : v1);
;     float2 w; w.x = odd ? r : v0; w.y = odd ? v1 : r;
;     *(float2*)(base + (size_t)(odd ? 1 : 0) * ld + (c - (odd ? 1 : 0))) = w;
;   }
;   {
;     float r = dpp_swap1(odd ? v2 : v3);
;     float2 w; w.x = odd ? r : v2; w.y = odd ? v3 : r;
;     *(float2*)(base + (size_t)(2 + (odd ? 1 : 0)) * ld + (c - (odd ? 1 : 0))) = w;
;   }
; }
;   __device__ __forceinline__ void operator()(f32x4 (&acc)[2][2][4][2], int brow, int bcol, int wr, int wc, int fr, int fq) const {
;     ...
; #pragma unroll
;     for (int ai = 0; ai < 2; ++ai)
; #pragma unroll
;       for (int m = 0; m < 4; ++m) {
;         int rl0 = ai * 128 + wr * 64 + m * 16 + fq * 4;
;         float4 r4 = *(const float4*)(rsl + rl0);
;         float rr[4] = {r4.x, r4.y, r4.z, r4.w};
; #pragma unroll
;         for (int bj = 0; bj < 2; ++bj)
; #pragma unroll
;           for (int n = 0; n < 2; ++n) {
;             int c = bcol + bj * 128 + wc * 32 + n * 16 + fr;
;             float gf = p.g_final[c];
;             store_rm4_f32(p.out + (size_t)(brow + rl0) * 1024, 1024, c, fr & 1, acc[ai][bj][m][n][0] * rr[0] * gf,
;                           acc[ai][bj][m][n][1] * rr[1] * gf, acc[ai][bj][m][n][2] * rr[2] * gf, acc[ai][bj][m][n][3] * rr[3] * gf);
;           }
;         __builtin_amdgcn_sched_barrier(0);
;       }
	v_cndmask_b32_e32 v225, v234, v225, vcc
	v_cndmask_b32_e32 v226, v226, v235, vcc
	v_cndmask_b32_e32 v227, v235, v227, vcc
	v_add_u32_e32 v138, 0x80000, v137
	v_add_u32_e32 v139, 0x82000, v137
	global_store_dwordx2 v138, v[212:213], s[100:101] nt
	global_store_dwordx2 v139, v[214:215], s[100:101] nt
	global_store_dwordx2 v138, v[216:217], s[100:101] offset:64 nt
	global_store_dwordx2 v139, v[218:219], s[100:101] offset:64 nt
	global_store_dwordx2 v138, v[220:221], s[100:101] offset:512 nt
	global_store_dwordx2 v139, v[222:223], s[100:101] offset:512 nt
	global_store_dwordx2 v138, v[224:225], s[100:101] offset:576 nt
	global_store_dwordx2 v139, v[226:227], s[100:101] offset:576 nt
	v_mul_f32_e32 v212, v32, v196
	v_mul_f32_e32 v213, v33, v197
	v_mul_f32_e32 v214, v34, v198
	v_mul_f32_e32 v215, v35, v199
	v_mul_f32_e32 v216, v36, v196
	v_mul_f32_e32 v217, v37, v197
	v_mul_f32_e32 v218, v38, v198
	v_mul_f32_e32 v219, v39, v199
	v_mul_f32_e32 v220, v44, v196
	v_mul_f32_e32 v221, v45, v197
	v_mul_f32_e32 v222, v46, v198
	v_mul_f32_e32 v223, v47, v199
	v_mul_f32_e32 v224, v40, v196
	v_mul_f32_e32 v225, v41, v197
	v_mul_f32_e32 v226, v42, v198
	v_mul_f32_e32 v227, v43, v199
	v_mul_f32_e32 v212, v212, v208
	v_mul_f32_e32 v213, v213, v208
	v_mul_f32_e32 v214, v214, v208
	v_mul_f32_e32 v215, v215, v208
	v_mul_f32_e32 v216, v216, v209
	v_mul_f32_e32 v217, v217, v209
	v_mul_f32_e32 v218, v218, v209
	v_mul_f32_e32 v219, v219, v209
	v_mul_f32_e32 v220, v220, v210
	v_mul_f32_e32 v221, v221, v210
	v_mul_f32_e32 v222, v222, v210
	v_mul_f32_e32 v223, v223, v210
	v_mul_f32_e32 v224, v224, v211
	v_mul_f32_e32 v225, v225, v211
	v_mul_f32_e32 v226, v226, v211
	v_mul_f32_e32 v227, v227, v211
	v_cndmask_b32_e32 v228, v213, v212, vcc
	v_cndmask_b32_e32 v229, v215, v214, vcc
	v_cndmask_b32_e32 v230, v217, v216, vcc
	v_cndmask_b32_e32 v231, v219, v218, vcc
	v_cndmask_b32_e32 v232, v221, v220, vcc
	v_cndmask_b32_e32 v233, v223, v222, vcc
	v_cndmask_b32_e32 v234, v225, v224, vcc
	v_cndmask_b32_e32 v235, v227, v226, vcc
	v_mov_b32_dpp v228, v228 quad_perm:[1,0,3,2] row_mask:0xf bank_mask:0xf bound_ctrl:1
	v_mov_b32_dpp v229, v229 quad_perm:[1,0,3,2] row_mask:0xf bank_mask:0xf bound_ctrl:1
	v_mov_b32_dpp v230, v230 quad_perm:[1,0,3,2] row_mask:0xf bank_mask:0xf bound_ctrl:1
	v_mov_b32_dpp v231, v231 quad_perm:[1,0,3,2] row_mask:0xf bank_mask:0xf bound_ctrl:1
	v_mov_b32_dpp v232, v232 quad_perm:[1,0,3,2] row_mask:0xf bank_mask:0xf bound_ctrl:1
	v_mov_b32_dpp v233, v233 quad_perm:[1,0,3,2] row_mask:0xf bank_mask:0xf bound_ctrl:1
	v_mov_b32_dpp v234, v234 quad_perm:[1,0,3,2] row_mask:0xf bank_mask:0xf bound_ctrl:1
	v_mov_b32_dpp v235, v235 quad_perm:[1,0,3,2] row_mask:0xf bank_mask:0xf bound_ctrl:1
	v_cndmask_b32_e32 v212, v212, v228, vcc
	v_cndmask_b32_e32 v213, v228, v213, vcc
	v_cndmask_b32_e32 v214, v214, v229, vcc
	v_cndmask_b32_e32 v215, v229, v215, vcc
	v_cndmask_b32_e32 v216, v216, v230, vcc
	v_cndmask_b32_e32 v217, v230, v217, vcc
	v_cndmask_b32_e32 v218, v218, v231, vcc
	v_cndmask_b32_e32 v219, v231, v219, vcc
	v_cndmask_b32_e32 v220, v220, v232, vcc
	v_cndmask_b32_e32 v221, v232, v221, vcc
	v_cndmask_b32_e32 v222, v222, v233, vcc
	v_cndmask_b32_e32 v223, v233, v223, vcc
	v_cndmask_b32_e32 v224, v224, v234, vcc
	v_cndmask_b32_e32 v225, v234, v225, vcc
	v_cndmask_b32_e32 v226, v226, v235, vcc
	v_cndmask_b32_e32 v227, v235, v227, vcc
	v_add_u32_e32 v138, 0x90000, v137
	v_add_u32_e32 v139, 0x92000, v137
	global_store_dwordx2 v138, v[212:213], s[100:101] nt
	global_store_dwordx2 v139, v[214:215], s[100:101] nt
	global_store_dwordx2 v138, v[216:217], s[100:101] offset:64 nt
	global_store_dwordx2 v139, v[218:219], s[100:101] offset:64 nt
	global_store_dwordx2 v138, v[220:221], s[100:101] offset:512 nt
	global_store_dwordx2 v139, v[222:223], s[100:101] offset:512 nt
	global_store_dwordx2 v138, v[224:225], s[100:101] offset:576 nt
	global_store_dwordx2 v139, v[226:227], s[100:101] offset:576 nt
	v_mul_f32_e32 v212, v16, v200
	v_mul_f32_e32 v213, v17, v201
	v_mul_f32_e32 v214, v18, v202
	v_mul_f32_e32 v215, v19, v203
	v_mul_f32_e32 v216, v20, v200
	v_mul_f32_e32 v217, v21, v201
	v_mul_f32_e32 v218, v22, v202
	v_mul_f32_e32 v219, v23, v203
	v_mul_f32_e32 v220, v28, v200
	v_mul_f32_e32 v221, v29, v201
	v_mul_f32_e32 v222, v30, v202
	v_mul_f32_e32 v223, v31, v203
	v_mul_f32_e32 v224, v24, v200
	v_mul_f32_e32 v225, v25, v201
	v_mul_f32_e32 v226, v26, v202
	v_mul_f32_e32 v227, v27, v203
	v_mul_f32_e32 v212, v212, v208
	v_mul_f32_e32 v213, v213, v208
	v_mul_f32_e32 v214, v214, v208
	v_mul_f32_e32 v215, v215, v208
	v_mul_f32_e32 v216, v216, v209
	v_mul_f32_e32 v217, v217, v209
	v_mul_f32_e32 v218, v218, v209
	v_mul_f32_e32 v219, v219, v209
	v_mul_f32_e32 v220, v220, v210
	v_mul_f32_e32 v221, v221, v210
	v_mul_f32_e32 v222, v222, v210
	v_mul_f32_e32 v223, v223, v210
	v_mul_f32_e32 v224, v224, v211
	v_mul_f32_e32 v225, v225, v211
	v_mul_f32_e32 v226, v226, v211
	v_mul_f32_e32 v227, v227, v211
	v_cndmask_b32_e32 v228, v213, v212, vcc
	v_cndmask_b32_e32 v229, v215, v214, vcc
	v_cndmask_b32_e32 v230, v217, v216, vcc
	v_cndmask_b32_e32 v231, v219, v218, vcc
	v_cndmask_b32_e32 v232, v221, v220, vcc
	v_cndmask_b32_e32 v233, v223, v222, vcc
	v_cndmask_b32_e32 v234, v225, v224, vcc
	v_cndmask_b32_e32 v235, v227, v226, vcc
; __device__ __forceinline__ void store_rm4_f32(float* base, size_t ld, int c, bool odd, float v0, float v1, float v2, float v3) {
;   {
;     float r = dpp_swap1(odd ? v0 : v1);
;     float2 w; w.x = odd ? r : v0; w.y = odd ? v1 : r;
;     *(float2*)(base + (size_t)(odd ? 1 : 0) * ld + (c - (odd ? 1 : 0))) = w;
;   }
;   {
;     float r = dpp_swap1(odd ? v2 : v3);
;     float2 w; w.x = odd ? r : v2; w.y = odd ? v3 : r;
;     *(float2*)(base + (size_t)(2 + (odd ? 1 : 0)) * ld + (c - (odd ? 1 : 0))) = w;
;   }
; }
;   __device__ __forceinline__ void operator()(f32x4 (&acc)[2][2][4][2], int brow, int bcol, int wr, int wc, int fr, int fq) const {
;     ...
; #pragma unroll
;     for (int ai = 0; ai < 2; ++ai)
; #pragma unroll
;       for (int m = 0; m < 4; ++m) {
;         int rl0 = ai * 128 + wr * 64 + m * 16 + fq * 4;
;         float4 r4 = *(const float4*)(rsl + rl0);
;         float rr[4] = {r4.x, r4.y, r4.z, r4.w};
; #pragma unroll
;         for (int bj = 0; bj < 2; ++bj)
; #pragma unroll
;           for (int n = 0; n < 2; ++n) {
;             int c = bcol + bj * 128 + wc * 32 + n * 16 + fr;
;             float gf = p.g_final[c];
;             store_rm4_f32(p.out + (size_t)(brow + rl0) * 1024, 1024, c, fr & 1, acc[ai][bj][m][n][0] * rr[0] * gf,
;                           acc[ai][bj][m][n][1] * rr[1] * gf, acc[ai][bj][m][n][2] * rr[2] * gf, acc[ai][bj][m][n][3] * rr[3] * gf);
;           }
;         __builtin_amdgcn_sched_barrier(0);
;       }
	v_mov_b32_dpp v228, v228 quad_perm:[1,0,3,2] row_mask:0xf bank_mask:0xf bound_ctrl:1
	v_mov_b32_dpp v229, v229 quad_perm:[1,0,3,2] row_mask:0xf bank_mask:0xf bound_ctrl:1
	v_mov_b32_dpp v230, v230 quad_perm:[1,0,3,2] row_mask:0xf bank_mask:0xf bound_ctrl:1
	v_mov_b32_dpp v231, v231 quad_perm:[1,0,3,2] row_mask:0xf bank_mask:0xf bound_ctrl:1
	v_mov_b32_dpp v232, v232 quad_perm:[1,0,3,2] row_mask:0xf bank_mask:0xf bound_ctrl:1
	v_mov_b32_dpp v233, v233 quad_perm:[1,0,3,2] row_mask:0xf bank_mask:0xf bound_ctrl:1
	v_mov_b32_dpp v234, v234 quad_perm:[1,0,3,2] row_mask:0xf bank_mask:0xf bound_ctrl:1
	v_mov_b32_dpp v235, v235 quad_perm:[1,0,3,2] row_mask:0xf bank_mask:0xf bound_ctrl:1
	v_cndmask_b32_e32 v212, v212, v228, vcc
	v_cndmask_b32_e32 v213, v228, v213, vcc
	v_cndmask_b32_e32 v214, v214, v229, vcc
	v_cndmask_b32_e32 v215, v229, v215, vcc
	v_cndmask_b32_e32 v216, v216, v230, vcc
	v_cndmask_b32_e32 v217, v230, v217, vcc
	v_cndmask_b32_e32 v218, v218, v231, vcc
	v_cndmask_b32_e32 v219, v231, v219, vcc
	v_cndmask_b32_e32 v220, v220, v232, vcc
	v_cndmask_b32_e32 v221, v232, v221, vcc
	v_cndmask_b32_e32 v222, v222, v233, vcc
	v_cndmask_b32_e32 v223, v233, v223, vcc
	v_cndmask_b32_e32 v224, v224, v234, vcc
	v_cndmask_b32_e32 v225, v234, v225, vcc
	v_cndmask_b32_e32 v226, v226, v235, vcc
	v_cndmask_b32_e32 v227, v235, v227, vcc
	v_add_u32_e32 v138, 0xa0000, v137
	v_add_u32_e32 v139, 0xa2000, v137
	global_store_dwordx2 v138, v[212:213], s[100:101] nt
	global_store_dwordx2 v139, v[214:215], s[100:101] nt
	global_store_dwordx2 v138, v[216:217], s[100:101] offset:64 nt
	global_store_dwordx2 v139, v[218:219], s[100:101] offset:64 nt
	global_store_dwordx2 v138, v[220:221], s[100:101] offset:512 nt
	global_store_dwordx2 v139, v[222:223], s[100:101] offset:512 nt
	global_store_dwordx2 v138, v[224:225], s[100:101] offset:576 nt
	global_store_dwordx2 v139, v[226:227], s[100:101] offset:576 nt
	v_mul_f32_e32 v212, v240, v204
	v_mul_f32_e32 v213, v241, v205
	v_mul_f32_e32 v214, v242, v206
	v_mul_f32_e32 v215, v243, v207
	v_mul_f32_e32 v216, v244, v204
	v_mul_f32_e32 v217, v245, v205
	v_mul_f32_e32 v218, v246, v206
	v_mul_f32_e32 v219, v247, v207
	v_mul_f32_e32 v220, v12, v204
	v_mul_f32_e32 v221, v13, v205
	v_mul_f32_e32 v222, v14, v206
	v_mul_f32_e32 v223, v15, v207
	v_mul_f32_e32 v224, v248, v204
	v_mul_f32_e32 v225, v249, v205
	v_mul_f32_e32 v226, v10, v206
	v_mul_f32_e32 v227, v11, v207
	v_mul_f32_e32 v212, v212, v208
	v_mul_f32_e32 v213, v213, v208
	v_mul_f32_e32 v214, v214, v208
	v_mul_f32_e32 v215, v215, v208
	v_mul_f32_e32 v216, v216, v209
	v_mul_f32_e32 v217, v217, v209
	v_mul_f32_e32 v218, v218, v209
	v_mul_f32_e32 v219, v219, v209
	v_mul_f32_e32 v220, v220, v210
	v_mul_f32_e32 v221, v221, v210
	v_mul_f32_e32 v222, v222, v210
	v_mul_f32_e32 v223, v223, v210
	v_mul_f32_e32 v224, v224, v211
	v_mul_f32_e32 v225, v225, v211
	v_mul_f32_e32 v226, v226, v211
	v_mul_f32_e32 v227, v227, v211
	v_cndmask_b32_e32 v228, v213, v212, vcc
	v_cndmask_b32_e32 v229, v215, v214, vcc
	v_cndmask_b32_e32 v230, v217, v216, vcc
	v_cndmask_b32_e32 v231, v219, v218, vcc
	v_cndmask_b32_e32 v232, v221, v220, vcc
	v_cndmask_b32_e32 v233, v223, v222, vcc
	v_cndmask_b32_e32 v234, v225, v224, vcc
	v_cndmask_b32_e32 v235, v227, v226, vcc
	v_mov_b32_dpp v228, v228 quad_perm:[1,0,3,2] row_mask:0xf bank_mask:0xf bound_ctrl:1
	v_mov_b32_dpp v229, v229 quad_perm:[1,0,3,2] row_mask:0xf bank_mask:0xf bound_ctrl:1
	v_mov_b32_dpp v230, v230 quad_perm:[1,0,3,2] row_mask:0xf bank_mask:0xf bound_ctrl:1
	v_mov_b32_dpp v231, v231 quad_perm:[1,0,3,2] row_mask:0xf bank_mask:0xf bound_ctrl:1
	v_mov_b32_dpp v232, v232 quad_perm:[1,0,3,2] row_mask:0xf bank_mask:0xf bound_ctrl:1
	v_mov_b32_dpp v233, v233 quad_perm:[1,0,3,2] row_mask:0xf bank_mask:0xf bound_ctrl:1
	v_mov_b32_dpp v234, v234 quad_perm:[1,0,3,2] row_mask:0xf bank_mask:0xf bound_ctrl:1
	v_mov_b32_dpp v235, v235 quad_perm:[1,0,3,2] row_mask:0xf bank_mask:0xf bound_ctrl:1
	v_cndmask_b32_e32 v212, v212, v228, vcc
	v_cndmask_b32_e32 v213, v228, v213, vcc
	v_cndmask_b32_e32 v214, v214, v229, vcc
	v_cndmask_b32_e32 v215, v229, v215, vcc
	v_cndmask_b32_e32 v216, v216, v230, vcc
	v_cndmask_b32_e32 v217, v230, v217, vcc
	v_cndmask_b32_e32 v218, v218, v231, vcc
	v_cndmask_b32_e32 v219, v231, v219, vcc
	v_cndmask_b32_e32 v220, v220, v232, vcc
	v_cndmask_b32_e32 v221, v232, v221, vcc
	v_cndmask_b32_e32 v222, v222, v233, vcc
	v_cndmask_b32_e32 v223, v233, v223, vcc
	v_cndmask_b32_e32 v224, v224, v234, vcc
	v_cndmask_b32_e32 v225, v234, v225, vcc
	v_cndmask_b32_e32 v226, v226, v235, vcc
	v_cndmask_b32_e32 v227, v235, v227, vcc
	v_add_u32_e32 v138, 0xb0000, v137
	v_add_u32_e32 v139, 0xb2000, v137
	global_store_dwordx2 v138, v[212:213], s[100:101] nt
	global_store_dwordx2 v139, v[214:215], s[100:101] nt
	global_store_dwordx2 v138, v[216:217], s[100:101] offset:64 nt
	global_store_dwordx2 v139, v[218:219], s[100:101] offset:64 nt
	global_store_dwordx2 v138, v[220:221], s[100:101] offset:512 nt
	global_store_dwordx2 v139, v[222:223], s[100:101] offset:512 nt
	global_store_dwordx2 v138, v[224:225], s[100:101] offset:576 nt
	global_store_dwordx2 v139, v[226:227], s[100:101] offset:576 nt
	s_waitcnt lgkmcnt(0)
	s_cmp_lg_u32 s45, 4
	s_mov_b32 s58, s47
	s_mov_b32 s59, s46
	s_mov_b32 s2, s45
	s_barrier
	s_cbranch_scc0 .LBB0_749
